# P5/P6 start stagger variant: odd XCDs start 1.4 us late
# speedup vs baseline: 1.0066x; 1.0035x over previous
; #define LAS __attribute__((address_space(3)))
;     DI bool next(int i, Unit& u) const {
;         const long L = (long)i * G + c; if (L >= nwg) return false;
;         int wgid = (int)L; { const int q = nwg / NXCD, r = nwg % NXCD, xcd = wgid % NXCD, off = wgid / NXCD; wgid = (xcd < r ? xcd * (q + 1) : r * (q + 1) + (xcd - r) * q) + off; }
;         const int nig = WGM * nN, gid = wgid / nig, fm = gid * WGM, gsz = (nM - fm) < WGM ? (nM - fm) : WGM;
;         u.pm = fm + ((wgid % nig) % gsz); u.pn = (wgid % nig) / gsz; return true;
; __global__ void __launch_bounds__(512, 2) mega(Params p) {
;     ...
;     if (PH(5)) {
;         pg8::Gemm g; g.A0 = (const bf16_t*)(p.ws + WS_ZG); g.A1 = (const bf16_t*)(p.ws + WS_YB) - 2048; g.B0 = (const bf16_t*)(p.ws + WS_WAT); g.B1 = (const bf16_t*)(p.ws + WS_WBT) - 2048;
;         g.lda = DM; g.ldb = DM; g.M = S; g.N = DM; g.K = 2 * DM; g.ksplit = DM / 64;
;         pg8::StaticOrder so; so.init(g.M, g.N, (int)gridDim.x, (int)blockIdx.x);
;         EpiMergeMid e; e.ws = p.ws;
;         pg8::gemm_phase<EpiMergeMid>((LAS unsigned char*)shm, g, so, e);
.LBB0_431:
	s_or_b64 exec, exec, s[4:5]
	v_cmp_gt_i32_e32 vcc, 6, v0
	v_cmp_lt_i32_e64 s[4:5], 5, v1
	s_and_b64 s[4:5], vcc, s[4:5]
	s_and_saveexec_b64 s[6:7], s[4:5]
	s_cbranch_execz .LBB0_456
	s_bitcmp1_b32 s2, 0
	s_cbranch_scc0 .Lp5_nostag
	s_sleep 38

; #define LAS __attribute__((address_space(3)))
;     DI bool next(int i, Unit& u) const {
;         const long L = (long)i * G + c; if (L >= nwg) return false;
;         int wgid = (int)L; { const int q = nwg / NXCD, r = nwg % NXCD, xcd = wgid % NXCD, off = wgid / NXCD; wgid = (xcd < r ? xcd * (q + 1) : r * (q + 1) + (xcd - r) * q) + off; }
;         const int nig = WGM * nN, gid = wgid / nig, fm = gid * WGM, gsz = (nM - fm) < WGM ? (nM - fm) : WGM;
;         u.pm = fm + ((wgid % nig) % gsz); u.pn = (wgid % nig) / gsz; return true;
; __global__ void __launch_bounds__(512, 2) mega(Params p) {
;     ...
;     if (PH(6)) {
;         pg8::Gemm g; g.A0 = (const bf16_t*)(p.ws + WS_MRG); g.A1 = g.A0; g.B0 = (const bf16_t*)(p.ws + WS_WOT); g.B1 = g.B0;
;         g.lda = DM; g.ldb = DM; g.M = S; g.N = DM; g.K = DM; g.ksplit = DM / 64;
;         pg8::StaticOrder so; so.init(g.M, g.N, (int)gridDim.x, (int)blockIdx.x);
;         EpiOut e; e.ws = p.ws;
;         pg8::gemm_phase<EpiOut>((LAS unsigned char*)shm, g, so, e);
.LBB0_506:
	s_or_b64 exec, exec, s[4:5]
	v_cmp_gt_i32_e32 vcc, 7, v0
	v_cmp_lt_i32_e64 s[4:5], 6, v1
	s_and_b64 s[4:5], vcc, s[4:5]
	s_and_saveexec_b64 s[8:9], s[4:5]
	s_cbranch_execz .LBB0_545
	s_bitcmp1_b32 s2, 0
	s_cbranch_scc0 .Lp6_nostag
	s_sleep 38
